# w24 + next tile's fourth A half-tile staged at epilogue top (before the stores), third first-iteration wait relaxed to vmcnt(24)
# baseline (speedup 1.0000x reference)
; #define PG8_STAGE(bufoff, gbase, voff) do { _Pragma("unroll") for (int _i = 0; _i < 2; ++_i) \
;         __builtin_amdgcn_global_load_lds((const unsigned*)((const char*)(gbase) + (voff)[_i]), (PG8_LAS unsigned*)(lds + (bufoff) + ldsw + _i * 8192), 16, 0, 0); } while (0)
; #define PG8_LDA(dst, b, h) do { _Pragma("unroll") for (int m = 0; m < 4; ++m) _Pragma("unroll") for (int k = 0; k < 2; ++k) dst[m][k] = *(const PG8_LAS bf16x8*)(lds + PG8_SA(b, h) + aoff + m * 2048 + k * 1024); } while (0)
; #define PG8_LDB(dst, b, h) do { _Pragma("unroll") for (int n = 0; n < 2; ++n) _Pragma("unroll") for (int k = 0; k < 2; ++k) dst[n][k] = *(const PG8_LAS bf16x8*)(lds + PG8_SB(b, h) + boff + n * 2048 + k * 1024); } while (0)
; #define PG8_SCHED __builtin_amdgcn_sched_barrier(0)
; template <class Epi, class Sched, bool ALIGN_EPI = false, bool SP2 = false>
; __device__ __forceinline__ void gemm_phase(PG8_LAS unsigned char* lds, const Gemm g, const Sched& S, const Epi& E) {
;     ...
;             PG8_LDB(B0, 0, 0); PG8_LDB(B1, 0, 1); PG8_SCHED; PG8_LDA(At, 0, 0); PG8_STAGE(PG8_SA(1, 1), a1 + hstep, voffA);
.LBB0_157:
	ds_read_b128 v[152:155], v149
	ds_read_b128 v[156:159], v149 offset:1024
	ds_read_b128 v[160:163], v149 offset:2048
	ds_read_b128 v[164:167], v149 offset:3072
	ds_read_b128 v[168:171], v150
	ds_read_b128 v[172:175], v150 offset:1024
	ds_read_b128 v[176:179], v150 offset:2048
	ds_read_b128 v[180:183], v150 offset:3072
	s_add_u32 s14, s76, 0xfffc0080
	s_addc_u32 s15, s77, -1
	s_cmp_eq_u32 s16, 12
	s_cselect_b32 s85, s45, s15
	s_cselect_b32 s84, vcc_lo, s14
	s_cselect_b32 s19, s43, s33
	s_cselect_b32 s18, vcc_hi, s5
	v_lshl_add_u64 v[144:145], s[76:77], 0, v[136:137]
	s_add_i32 m0, s75, 0xc000
	ds_read_b128 v[184:187], v151
	ds_read_b128 v[188:191], v151 offset:1024
	ds_read_b128 v[192:195], v151 offset:2048
	ds_read_b128 v[196:199], v151 offset:3072
	ds_read_b128 v[200:203], v151 offset:4096
	ds_read_b128 v[204:207], v151 offset:5120
	ds_read_b128 v[218:221], v151 offset:6144
	ds_read_b128 v[222:225], v151 offset:7168
	s_cmp_lg_u32 s100, 0
	s_cbranch_scc1 .Lsk2
	global_load_lds_dwordx4 v[144:145], off
	v_lshl_add_u64 v[144:145], s[76:77], 0, v[138:139]
	s_add_i32 m0, s75, 0xe000
	s_nop 0
	global_load_lds_dwordx4 v[144:145], off
.Lsk2:
	s_cmp_eq_u32 s100, 0
	s_cbranch_scc1 .Lw8_2a
	s_waitcnt vmcnt(24)
	s_branch .Lwd_2a

; #define PG8_STAGE(bufoff, gbase, voff) do { _Pragma("unroll") for (int _i = 0; _i < 2; ++_i) \
;         __builtin_amdgcn_global_load_lds((const unsigned*)((const char*)(gbase) + (voff)[_i]), (PG8_LAS unsigned*)(lds + (bufoff) + ldsw + _i * 8192), 16, 0, 0); } while (0)
; #define PG8_LDA(dst, b, h) do { _Pragma("unroll") for (int m = 0; m < 4; ++m) _Pragma("unroll") for (int k = 0; k < 2; ++k) dst[m][k] = *(const PG8_LAS bf16x8*)(lds + PG8_SA(b, h) + aoff + m * 2048 + k * 1024); } while (0)
; #define PG8_MMA(ai, bj, At, Bt) do { __builtin_amdgcn_s_setprio(1); _Pragma("unroll") for (int m = 0; m < 4; ++m) _Pragma("unroll") for (int n = 0; n < 2; ++n) _Pragma("unroll") for (int k = 0; k < 2; ++k) \
;         acc[ai][bj][m][n] = __builtin_amdgcn_mfma_f32_16x16x32_bf16(Bt[n][k], At[m][k], acc[ai][bj][m][n], 0, 0, 0); __builtin_amdgcn_s_setprio(0); } while (0)
; #define PG8_WAIT_V(n) asm volatile("s_waitcnt vmcnt(" #n ")" ::: "memory")
; #define PG8_WAIT_L(n) asm volatile("s_waitcnt lgkmcnt(" #n ")" ::: "memory")
; #define PG8_BAR __builtin_amdgcn_s_barrier()
; #define PG8_SCHED __builtin_amdgcn_sched_barrier(0)
; template <class Epi, class Sched, bool ALIGN_EPI = false, bool SP2 = false>
; __device__ __forceinline__ void gemm_phase(PG8_LAS unsigned char* lds, const Gemm g, const Sched& S, const Epi& E) {
;     ...
;             PG8_WAIT_V(8); PG8_WAIT_L(0); PG8_BAR; PG8_MMA(0, 0, At, B0); PG8_MMA(0, 1, At, B1); PG8_BAR; PG8_SCHED;
;             PG8_LDA(At, 0, 1); PG8_STAGE(PG8_SB(0, 0), b2, voffB); PG8_STAGE(PG8_SB(0, 1), b2 + hstep, voffB); PG8_STAGE(PG8_SA(0, 0), a2, voffA);
;             PG8_WAIT_V(8); PG8_WAIT_L(0); PG8_BAR; PG8_MMA(1, 0, At, B0); PG8_MMA(1, 1, At, B1); PG8_BAR; PG8_SCHED;
.Lwd_2b:
	s_waitcnt lgkmcnt(0)
	s_barrier
	s_setprio 1
	s_waitcnt lgkmcnt(0)
	v_mfma_f32_16x16x32_bf16 v[60:63], v[152:155], v[184:187], v[60:63]
	v_mfma_f32_16x16x32_bf16 v[56:59], v[160:163], v[184:187], v[56:59]
	v_mfma_f32_16x16x32_bf16 v[48:51], v[152:155], v[192:195], v[48:51]
	v_mfma_f32_16x16x32_bf16 v[40:43], v[160:163], v[192:195], v[40:43]
	v_mfma_f32_16x16x32_bf16 v[32:35], v[152:155], v[200:203], v[32:35]
	v_mfma_f32_16x16x32_bf16 v[24:27], v[160:163], v[200:203], v[24:27]
	v_mfma_f32_16x16x32_bf16 v[16:19], v[152:155], v[218:221], v[16:19]
	v_mfma_f32_16x16x32_bf16 v[8:11], v[160:163], v[218:221], v[8:11]
	v_mfma_f32_16x16x32_bf16 v[60:63], v[156:159], v[188:191], v[60:63]
	v_mfma_f32_16x16x32_bf16 v[56:59], v[164:167], v[188:191], v[56:59]
	v_mfma_f32_16x16x32_bf16 v[48:51], v[156:159], v[196:199], v[48:51]
	v_mfma_f32_16x16x32_bf16 v[40:43], v[164:167], v[196:199], v[40:43]
	v_mfma_f32_16x16x32_bf16 v[32:35], v[156:159], v[204:207], v[32:35]
	v_mfma_f32_16x16x32_bf16 v[24:27], v[164:167], v[204:207], v[24:27]
	v_mfma_f32_16x16x32_bf16 v[16:19], v[156:159], v[222:225], v[16:19]
	v_mfma_f32_16x16x32_bf16 v[8:11], v[164:167], v[222:225], v[8:11]
	s_setprio 0
	s_setprio 1
	v_mfma_f32_16x16x32_bf16 v[52:55], v[168:171], v[184:187], v[52:55]
	v_mfma_f32_16x16x32_bf16 v[44:47], v[176:179], v[184:187], v[44:47]
	v_mfma_f32_16x16x32_bf16 v[36:39], v[168:171], v[192:195], v[36:39]
	v_mfma_f32_16x16x32_bf16 v[28:31], v[176:179], v[192:195], v[28:31]
	v_mfma_f32_16x16x32_bf16 v[20:23], v[168:171], v[200:203], v[20:23]
	v_mfma_f32_16x16x32_bf16 v[12:15], v[176:179], v[200:203], v[12:15]
	v_mfma_f32_16x16x32_bf16 v[4:7], v[168:171], v[218:221], v[4:7]
	v_mfma_f32_16x16x32_bf16 v[0:3], v[176:179], v[218:221], v[0:3]
	v_mfma_f32_16x16x32_bf16 v[52:55], v[172:175], v[188:191], v[52:55]
	v_mfma_f32_16x16x32_bf16 v[44:47], v[180:183], v[188:191], v[44:47]
	v_mfma_f32_16x16x32_bf16 v[36:39], v[172:175], v[196:199], v[36:39]
	v_mfma_f32_16x16x32_bf16 v[28:31], v[180:183], v[196:199], v[28:31]
	v_mfma_f32_16x16x32_bf16 v[20:23], v[172:175], v[204:207], v[20:23]
	v_mfma_f32_16x16x32_bf16 v[12:15], v[180:183], v[204:207], v[12:15]
	v_mfma_f32_16x16x32_bf16 v[4:7], v[172:175], v[222:225], v[4:7]
	v_mfma_f32_16x16x32_bf16 v[0:3], v[180:183], v[222:225], v[0:3]
	s_setprio 0
	s_barrier
	s_add_i32 s17, 0, 0x18000
	s_add_i32 s24, 0, 0x1c000
	v_add_u32_e32 v164, s17, v147
	v_add_u32_e32 v180, s24, v147
	ds_read_b128 v[152:155], v164
	ds_read_b128 v[156:159], v164 offset:1024
	ds_read_b128 v[160:163], v164 offset:2048
	ds_read_b128 v[164:167], v164 offset:3072
	ds_read_b128 v[168:171], v180
	ds_read_b128 v[172:175], v180 offset:1024
	ds_read_b128 v[176:179], v180 offset:2048
	ds_read_b128 v[180:183], v180 offset:3072
	s_add_u32 s14, s84, 0x40000
	s_addc_u32 s15, s85, 0
	s_mov_b32 m0, s89
	v_lshl_add_u64 v[232:233], s[14:15], 0, v[134:135]
	ds_read_b128 v[184:187], v151 offset:32768
	ds_read_b128 v[188:191], v151 offset:33792
	ds_read_b128 v[192:195], v151 offset:34816
	ds_read_b128 v[196:199], v151 offset:35840
	ds_read_b128 v[200:203], v151 offset:36864
	ds_read_b128 v[204:207], v151 offset:37888
	ds_read_b128 v[218:221], v151 offset:38912
	ds_read_b128 v[222:225], v151 offset:39936
	global_load_lds_dwordx4 v[232:233], off
	v_lshl_add_u64 v[232:233], s[14:15], 0, v[130:131]
	s_mov_b32 m0, s90
	s_nop 0
	global_load_lds_dwordx4 v[232:233], off
	s_cmp_eq_u32 s100, 0
	s_cbranch_scc1 .Lw8_2c
	s_waitcnt vmcnt(24)
	s_branch .Lwd_2c

; #define PG8_STAGE(bufoff, gbase, voff) do { _Pragma("unroll") for (int _i = 0; _i < 2; ++_i) \
;         __builtin_amdgcn_global_load_lds((const unsigned*)((const char*)(gbase) + (voff)[_i]), (PG8_LAS unsigned*)(lds + (bufoff) + ldsw + _i * 8192), 16, 0, 0); } while (0)
; #define PG8_LDA(dst, b, h) do { _Pragma("unroll") for (int m = 0; m < 4; ++m) _Pragma("unroll") for (int k = 0; k < 2; ++k) dst[m][k] = *(const PG8_LAS bf16x8*)(lds + PG8_SA(b, h) + aoff + m * 2048 + k * 1024); } while (0)
; #define PG8_LDB(dst, b, h) do { _Pragma("unroll") for (int n = 0; n < 2; ++n) _Pragma("unroll") for (int k = 0; k < 2; ++k) dst[n][k] = *(const PG8_LAS bf16x8*)(lds + PG8_SB(b, h) + boff + n * 2048 + k * 1024); } while (0)
; #define PG8_MMA(ai, bj, At, Bt) do { __builtin_amdgcn_s_setprio(1); _Pragma("unroll") for (int m = 0; m < 4; ++m) _Pragma("unroll") for (int n = 0; n < 2; ++n) _Pragma("unroll") for (int k = 0; k < 2; ++k) \
;         acc[ai][bj][m][n] = __builtin_amdgcn_mfma_f32_16x16x32_bf16(Bt[n][k], At[m][k], acc[ai][bj][m][n], 0, 0, 0); __builtin_amdgcn_s_setprio(0); } while (0)
; #define PG8_WAIT_V(n) asm volatile("s_waitcnt vmcnt(" #n ")" ::: "memory")
; #define PG8_WAIT_L(n) asm volatile("s_waitcnt lgkmcnt(" #n ")" ::: "memory")
; #define PG8_BAR __builtin_amdgcn_s_barrier()
; #define PG8_SCHED __builtin_amdgcn_sched_barrier(0)
; template <class Epi, class Sched, bool ALIGN_EPI = false, bool SP2 = false>
; __device__ __forceinline__ void gemm_phase(PG8_LAS unsigned char* lds, const Gemm g, const Sched& S, const Epi& E) {
;     ...
;             PG8_LDB(B0, 0, 0); PG8_LDB(B1, 0, 1); PG8_SCHED; PG8_LDA(At, 0, 0); PG8_STAGE(PG8_SA(1, 1), a1 + hstep, voffA);
;     ...
;             PG8_WAIT_V(8); PG8_WAIT_L(0); PG8_BAR; PG8_MMA(1, 0, At, B0); PG8_MMA(1, 1, At, B1); PG8_BAR; PG8_SCHED;
;             PG8_LDB(B0, 1, 0); PG8_LDB(B1, 1, 1); PG8_SCHED; PG8_LDA(At, 1, 0); PG8_STAGE(PG8_SA(0, 1), a2 + hstep, voffA);
;             PG8_WAIT_V(8); PG8_WAIT_L(0); PG8_BAR; PG8_MMA(0, 0, At, B0); PG8_MMA(0, 1, At, B1); PG8_BAR; PG8_SCHED;
;             PG8_LDA(At, 1, 1); PG8_STAGE(PG8_SB(1, 0), b3, voffB); PG8_STAGE(PG8_SB(1, 1), b3 + hstep, voffB); PG8_STAGE(PG8_SA(1, 0), a3, voffA);
;             PG8_WAIT_V(8); PG8_WAIT_L(0); PG8_BAR; PG8_MMA(1, 0, At, B0); PG8_MMA(1, 1, At, B1); PG8_BAR; PG8_SCHED;
.Lwd_2c:
	s_mov_b32 s100, 0
	s_waitcnt lgkmcnt(0)
	s_barrier
	s_setprio 1
	s_waitcnt lgkmcnt(0)
	v_mfma_f32_16x16x32_bf16 v[124:127], v[152:155], v[184:187], v[124:127]
	v_mfma_f32_16x16x32_bf16 v[120:123], v[160:163], v[184:187], v[120:123]
	v_mfma_f32_16x16x32_bf16 v[112:115], v[152:155], v[192:195], v[112:115]
	v_mfma_f32_16x16x32_bf16 v[104:107], v[160:163], v[192:195], v[104:107]
	v_mfma_f32_16x16x32_bf16 v[96:99], v[152:155], v[200:203], v[96:99]
	v_mfma_f32_16x16x32_bf16 v[88:91], v[160:163], v[200:203], v[88:91]
	v_mfma_f32_16x16x32_bf16 v[80:83], v[152:155], v[218:221], v[80:83]
	v_mfma_f32_16x16x32_bf16 v[72:75], v[160:163], v[218:221], v[72:75]
	v_mfma_f32_16x16x32_bf16 v[124:127], v[156:159], v[188:191], v[124:127]
	v_mfma_f32_16x16x32_bf16 v[120:123], v[164:167], v[188:191], v[120:123]
	v_mfma_f32_16x16x32_bf16 v[112:115], v[156:159], v[196:199], v[112:115]
	v_mfma_f32_16x16x32_bf16 v[104:107], v[164:167], v[196:199], v[104:107]
	v_mfma_f32_16x16x32_bf16 v[96:99], v[156:159], v[204:207], v[96:99]
	v_mfma_f32_16x16x32_bf16 v[88:91], v[164:167], v[204:207], v[88:91]
	v_mfma_f32_16x16x32_bf16 v[80:83], v[156:159], v[222:225], v[80:83]
	v_mfma_f32_16x16x32_bf16 v[72:75], v[164:167], v[222:225], v[72:75]
	s_setprio 0
	s_setprio 1
	v_mfma_f32_16x16x32_bf16 v[116:119], v[168:171], v[184:187], v[116:119]
	v_mfma_f32_16x16x32_bf16 v[108:111], v[176:179], v[184:187], v[108:111]
	v_mfma_f32_16x16x32_bf16 v[100:103], v[168:171], v[192:195], v[100:103]
	v_mfma_f32_16x16x32_bf16 v[92:95], v[176:179], v[192:195], v[92:95]
	v_mfma_f32_16x16x32_bf16 v[84:87], v[168:171], v[200:203], v[84:87]
	v_mfma_f32_16x16x32_bf16 v[76:79], v[176:179], v[200:203], v[76:79]
	v_mfma_f32_16x16x32_bf16 v[68:71], v[168:171], v[218:221], v[68:71]
	v_mfma_f32_16x16x32_bf16 v[64:67], v[176:179], v[218:221], v[64:67]
	v_mfma_f32_16x16x32_bf16 v[116:119], v[172:175], v[188:191], v[116:119]
	v_mfma_f32_16x16x32_bf16 v[108:111], v[180:183], v[188:191], v[108:111]
	v_mfma_f32_16x16x32_bf16 v[100:103], v[172:175], v[196:199], v[100:103]
	v_mfma_f32_16x16x32_bf16 v[92:95], v[180:183], v[196:199], v[92:95]
	v_mfma_f32_16x16x32_bf16 v[84:87], v[172:175], v[204:207], v[84:87]
	v_mfma_f32_16x16x32_bf16 v[76:79], v[180:183], v[204:207], v[76:79]
	v_mfma_f32_16x16x32_bf16 v[68:71], v[172:175], v[222:225], v[68:71]
	v_mfma_f32_16x16x32_bf16 v[64:67], v[180:183], v[222:225], v[64:67]
	s_setprio 0
	s_barrier
	s_add_i32 s14, s17, s86
	v_lshl_add_u64 v[144:145], v[144:145], 0, s[22:23]
	s_mov_b32 m0, s14
	ds_read_b128 v[184:187], v151 offset:49152
	ds_read_b128 v[188:191], v151 offset:50176
	ds_read_b128 v[192:195], v151 offset:51200
	ds_read_b128 v[196:199], v151 offset:52224
	ds_read_b128 v[200:203], v151 offset:53248
	ds_read_b128 v[204:207], v151 offset:54272
	ds_read_b128 v[218:221], v151 offset:55296
	ds_read_b128 v[222:225], v151 offset:56320
	global_load_lds_dwordx4 v[144:145], off
	s_add_i32 m0, s14, 0x2000
	s_add_u32 s14, s18, 0x40080
	v_lshl_add_u64 v[144:145], v[226:227], 0, s[22:23]
	s_addc_u32 s15, s19, 0
	s_add_i32 s17, s24, s86
	global_load_lds_dwordx4 v[144:145], off
	v_lshl_add_u64 v[144:145], s[14:15], 0, v[132:133]
	s_mov_b32 m0, s17
	s_nop 0
	global_load_lds_dwordx4 v[144:145], off
	v_lshl_add_u64 v[144:145], s[14:15], 0, v[128:129]
	s_add_i32 m0, s17, 0x2000
	s_nop 0
	global_load_lds_dwordx4 v[144:145], off
	v_lshl_add_u64 v[144:145], v[228:229], 0, s[22:23]
	s_mov_b32 m0, s92
	s_nop 0
	global_load_lds_dwordx4 v[144:145], off
	v_lshl_add_u64 v[144:145], v[230:231], 0, s[22:23]
	s_mov_b32 m0, s93
	s_nop 0
	global_load_lds_dwordx4 v[144:145], off
	s_waitcnt vmcnt(8)
	s_waitcnt lgkmcnt(0)
	s_barrier
	s_setprio 1
	s_waitcnt lgkmcnt(0)
	v_mfma_f32_16x16x32_bf16 v[60:63], v[152:155], v[184:187], v[60:63]
	v_mfma_f32_16x16x32_bf16 v[56:59], v[160:163], v[184:187], v[56:59]
	v_mfma_f32_16x16x32_bf16 v[48:51], v[152:155], v[192:195], v[48:51]
	v_mfma_f32_16x16x32_bf16 v[40:43], v[160:163], v[192:195], v[40:43]
	v_mfma_f32_16x16x32_bf16 v[32:35], v[152:155], v[200:203], v[32:35]
	v_mfma_f32_16x16x32_bf16 v[24:27], v[160:163], v[200:203], v[24:27]
	v_mfma_f32_16x16x32_bf16 v[16:19], v[152:155], v[218:221], v[16:19]
	v_mfma_f32_16x16x32_bf16 v[8:11], v[160:163], v[218:221], v[8:11]
	v_mfma_f32_16x16x32_bf16 v[60:63], v[156:159], v[188:191], v[60:63]
	v_mfma_f32_16x16x32_bf16 v[56:59], v[164:167], v[188:191], v[56:59]
	v_mfma_f32_16x16x32_bf16 v[48:51], v[156:159], v[196:199], v[48:51]
	v_mfma_f32_16x16x32_bf16 v[40:43], v[164:167], v[196:199], v[40:43]
	v_mfma_f32_16x16x32_bf16 v[32:35], v[156:159], v[204:207], v[32:35]
	v_mfma_f32_16x16x32_bf16 v[24:27], v[164:167], v[204:207], v[24:27]
	v_mfma_f32_16x16x32_bf16 v[16:19], v[156:159], v[222:225], v[16:19]
	v_mfma_f32_16x16x32_bf16 v[8:11], v[164:167], v[222:225], v[8:11]
	s_setprio 0
	s_setprio 1
	v_mfma_f32_16x16x32_bf16 v[52:55], v[168:171], v[184:187], v[52:55]
	v_mfma_f32_16x16x32_bf16 v[44:47], v[176:179], v[184:187], v[44:47]
	v_mfma_f32_16x16x32_bf16 v[36:39], v[168:171], v[192:195], v[36:39]
	v_mfma_f32_16x16x32_bf16 v[28:31], v[176:179], v[192:195], v[28:31]
	v_mfma_f32_16x16x32_bf16 v[20:23], v[168:171], v[200:203], v[20:23]
	v_mfma_f32_16x16x32_bf16 v[12:15], v[176:179], v[200:203], v[12:15]
	v_mfma_f32_16x16x32_bf16 v[4:7], v[168:171], v[218:221], v[4:7]
	v_mfma_f32_16x16x32_bf16 v[0:3], v[176:179], v[218:221], v[0:3]
	v_mfma_f32_16x16x32_bf16 v[52:55], v[172:175], v[188:191], v[52:55]
	v_mfma_f32_16x16x32_bf16 v[44:47], v[180:183], v[188:191], v[44:47]
	v_mfma_f32_16x16x32_bf16 v[36:39], v[172:175], v[196:199], v[36:39]
	v_mfma_f32_16x16x32_bf16 v[28:31], v[180:183], v[196:199], v[28:31]
	v_mfma_f32_16x16x32_bf16 v[20:23], v[172:175], v[204:207], v[20:23]
	v_mfma_f32_16x16x32_bf16 v[12:15], v[180:183], v[204:207], v[12:15]
	v_mfma_f32_16x16x32_bf16 v[4:7], v[172:175], v[222:225], v[4:7]
	v_mfma_f32_16x16x32_bf16 v[0:3], v[180:183], v[222:225], v[0:3]
	s_setprio 0
	s_barrier
	s_add_i32 s16, s16, 2
	s_add_u32 s76, s76, 0x100
	s_addc_u32 s77, s77, 0
	s_add_u32 s5, s5, 0x100
	s_addc_u32 s33, s33, 0
	s_cmp_gt_u32 s16, 13
	s_cbranch_scc0 .LBB0_157
	s_and_b64 vcc, exec, s[38:39]
	s_cbranch_vccz .LBB0_160
	s_barrier
.LBB0_160:
	s_cmp_eq_u64 s[36:37], 0
	s_cbranch_scc1 .Les2_skip
	s_mov_b32 s101, m0
	s_add_u32 s98, s50, 0x40080
	s_addc_u32 s99, s51, 0
	v_lshl_add_u64 v[250:251], s[98:99], 0, v[136:137]
	s_add_i32 m0, s75, 0xc000
	s_nop 0
	global_load_lds_dwordx4 v[250:251], off
	v_lshl_add_u64 v[250:251], s[98:99], 0, v[138:139]
	s_add_i32 m0, s75, 0xe000
	s_nop 0
	global_load_lds_dwordx4 v[250:251], off
	s_mov_b32 m0, s101

; #define PG8_STAGE(bufoff, gbase, voff) do { _Pragma("unroll") for (int _i = 0; _i < 2; ++_i) \
;         __builtin_amdgcn_global_load_lds((const unsigned*)((const char*)(gbase) + (voff)[_i]), (PG8_LAS unsigned*)(lds + (bufoff) + ldsw + _i * 8192), 16, 0, 0); } while (0)
; #define PG8_LDA(dst, b, h) do { _Pragma("unroll") for (int m = 0; m < 4; ++m) _Pragma("unroll") for (int k = 0; k < 2; ++k) dst[m][k] = *(const PG8_LAS bf16x8*)(lds + PG8_SA(b, h) + aoff + m * 2048 + k * 1024); } while (0)
; #define PG8_LDB(dst, b, h) do { _Pragma("unroll") for (int n = 0; n < 2; ++n) _Pragma("unroll") for (int k = 0; k < 2; ++k) dst[n][k] = *(const PG8_LAS bf16x8*)(lds + PG8_SB(b, h) + boff + n * 2048 + k * 1024); } while (0)
; #define PG8_SCHED __builtin_amdgcn_sched_barrier(0)
; template <class Epi, class Sched, bool ALIGN_EPI = false, bool SP2 = false>
; __device__ __forceinline__ void gemm_phase(PG8_LAS unsigned char* lds, const Gemm g, const Sched& S, const Epi& E) {
;     ...
;             PG8_LDB(B0, 0, 0); PG8_LDB(B1, 0, 1); PG8_SCHED; PG8_LDA(At, 0, 0); PG8_STAGE(PG8_SA(1, 1), a1 + hstep, voffA);
.LBB0_637:
	ds_read_b128 v[72:75], v198
	ds_read_b128 v[84:87], v198 offset:1024
	ds_read_b128 v[96:99], v198 offset:2048
	ds_read_b128 v[100:103], v198 offset:3072
	ds_read_b128 v[112:115], v199
	ds_read_b128 v[116:119], v199 offset:1024
	ds_read_b128 v[128:131], v199 offset:2048
	ds_read_b128 v[140:143], v199 offset:3072
	s_add_u32 s14, s38, 0xfffc0080
	s_addc_u32 s15, s39, -1
	s_cmp_eq_u32 s16, 12
	s_cselect_b32 s41, s55, s15
	s_cselect_b32 s40, s68, s14
	s_cselect_b32 s19, s53, s33
	s_cselect_b32 s18, s69, s72
	v_lshl_add_u64 v[206:207], s[38:39], 0, v[176:177]
	s_add_i32 m0, s61, 0xc000
	ds_read_b128 v[184:187], v200
	ds_read_b128 v[188:191], v200 offset:1024
	ds_read_b128 v[192:195], v200 offset:2048
	ds_read_b128 v[202:205], v200 offset:3072
	ds_read_b128 v[218:221], v200 offset:4096
	ds_read_b128 v[222:225], v200 offset:5120
	ds_read_b128 v[226:229], v200 offset:6144
	ds_read_b128 v[230:233], v200 offset:7168
	s_cmp_lg_u32 s100, 0
	s_cbranch_scc1 .Lsk8
	global_load_lds_dwordx4 v[206:207], off
	v_lshl_add_u64 v[206:207], s[38:39], 0, v[178:179]
	s_add_i32 m0, s61, 0xe000
	s_nop 0
	global_load_lds_dwordx4 v[206:207], off

; #define PG8_STAGE(bufoff, gbase, voff) do { _Pragma("unroll") for (int _i = 0; _i < 2; ++_i) \
;         __builtin_amdgcn_global_load_lds((const unsigned*)((const char*)(gbase) + (voff)[_i]), (PG8_LAS unsigned*)(lds + (bufoff) + ldsw + _i * 8192), 16, 0, 0); } while (0)
; #define PG8_LDA(dst, b, h) do { _Pragma("unroll") for (int m = 0; m < 4; ++m) _Pragma("unroll") for (int k = 0; k < 2; ++k) dst[m][k] = *(const PG8_LAS bf16x8*)(lds + PG8_SA(b, h) + aoff + m * 2048 + k * 1024); } while (0)
; #define PG8_MMA(ai, bj, At, Bt) do { __builtin_amdgcn_s_setprio(1); _Pragma("unroll") for (int m = 0; m < 4; ++m) _Pragma("unroll") for (int n = 0; n < 2; ++n) _Pragma("unroll") for (int k = 0; k < 2; ++k) \
;         acc[ai][bj][m][n] = __builtin_amdgcn_mfma_f32_16x16x32_bf16(Bt[n][k], At[m][k], acc[ai][bj][m][n], 0, 0, 0); __builtin_amdgcn_s_setprio(0); } while (0)
; #define PG8_WAIT_V(n) asm volatile("s_waitcnt vmcnt(" #n ")" ::: "memory")
; #define PG8_WAIT_L(n) asm volatile("s_waitcnt lgkmcnt(" #n ")" ::: "memory")
; #define PG8_BAR __builtin_amdgcn_s_barrier()
; #define PG8_SCHED __builtin_amdgcn_sched_barrier(0)
; template <class Epi, class Sched, bool ALIGN_EPI = false, bool SP2 = false>
; __device__ __forceinline__ void gemm_phase(PG8_LAS unsigned char* lds, const Gemm g, const Sched& S, const Epi& E) {
;     ...
;             PG8_WAIT_V(8); PG8_WAIT_L(0); PG8_BAR; PG8_MMA(0, 0, At, B0); PG8_MMA(0, 1, At, B1); PG8_BAR; PG8_SCHED;
;             PG8_LDA(At, 0, 1); PG8_STAGE(PG8_SB(0, 0), b2, voffB); PG8_STAGE(PG8_SB(0, 1), b2 + hstep, voffB); PG8_STAGE(PG8_SA(0, 0), a2, voffA);
;             PG8_WAIT_V(8); PG8_WAIT_L(0); PG8_BAR; PG8_MMA(1, 0, At, B0); PG8_MMA(1, 1, At, B1); PG8_BAR; PG8_SCHED;
.Lwd_8b:
	s_waitcnt lgkmcnt(0)
	s_barrier
	s_setprio 1
	s_waitcnt lgkmcnt(0)
	v_mfma_f32_16x16x32_bf16 v[60:63], v[72:75], v[184:187], v[60:63]
	v_mfma_f32_16x16x32_bf16 v[56:59], v[96:99], v[184:187], v[56:59]
	v_mfma_f32_16x16x32_bf16 v[44:47], v[72:75], v[192:195], v[44:47]
	v_mfma_f32_16x16x32_bf16 v[40:43], v[96:99], v[192:195], v[40:43]
	v_mfma_f32_16x16x32_bf16 v[28:31], v[72:75], v[218:221], v[28:31]
	v_mfma_f32_16x16x32_bf16 v[24:27], v[96:99], v[218:221], v[24:27]
	v_mfma_f32_16x16x32_bf16 v[12:15], v[72:75], v[226:229], v[12:15]
	v_mfma_f32_16x16x32_bf16 v[8:11], v[96:99], v[226:229], v[8:11]
	v_mfma_f32_16x16x32_bf16 v[60:63], v[84:87], v[188:191], v[60:63]
	v_mfma_f32_16x16x32_bf16 v[56:59], v[100:103], v[188:191], v[56:59]
	v_mfma_f32_16x16x32_bf16 v[44:47], v[84:87], v[202:205], v[44:47]
	v_mfma_f32_16x16x32_bf16 v[40:43], v[100:103], v[202:205], v[40:43]
	v_mfma_f32_16x16x32_bf16 v[28:31], v[84:87], v[222:225], v[28:31]
	v_mfma_f32_16x16x32_bf16 v[24:27], v[100:103], v[222:225], v[24:27]
	v_mfma_f32_16x16x32_bf16 v[12:15], v[84:87], v[230:233], v[12:15]
	v_mfma_f32_16x16x32_bf16 v[8:11], v[100:103], v[230:233], v[8:11]
	s_setprio 0
	s_setprio 1
	v_mfma_f32_16x16x32_bf16 v[52:55], v[112:115], v[184:187], v[52:55]
	v_mfma_f32_16x16x32_bf16 v[48:51], v[128:131], v[184:187], v[48:51]
	v_mfma_f32_16x16x32_bf16 v[36:39], v[112:115], v[192:195], v[36:39]
	v_mfma_f32_16x16x32_bf16 v[32:35], v[128:131], v[192:195], v[32:35]
	v_mfma_f32_16x16x32_bf16 v[20:23], v[112:115], v[218:221], v[20:23]
	v_mfma_f32_16x16x32_bf16 v[16:19], v[128:131], v[218:221], v[16:19]
	v_mfma_f32_16x16x32_bf16 v[4:7], v[112:115], v[226:229], v[4:7]
	v_mfma_f32_16x16x32_bf16 v[0:3], v[128:131], v[226:229], v[0:3]
	v_mfma_f32_16x16x32_bf16 v[52:55], v[116:119], v[188:191], v[52:55]
	v_mfma_f32_16x16x32_bf16 v[48:51], v[140:143], v[188:191], v[48:51]
	v_mfma_f32_16x16x32_bf16 v[36:39], v[116:119], v[202:205], v[36:39]
	v_mfma_f32_16x16x32_bf16 v[32:35], v[140:143], v[202:205], v[32:35]
	v_mfma_f32_16x16x32_bf16 v[20:23], v[116:119], v[222:225], v[20:23]
	v_mfma_f32_16x16x32_bf16 v[16:19], v[140:143], v[222:225], v[16:19]
	v_mfma_f32_16x16x32_bf16 v[4:7], v[116:119], v[230:233], v[4:7]
	v_mfma_f32_16x16x32_bf16 v[0:3], v[140:143], v[230:233], v[0:3]
	s_setprio 0
	s_barrier
	s_add_i32 s17, 0, 0x18000
	s_add_i32 s24, 0, 0x1c000
	v_add_u32_e32 v100, s17, v197
	v_add_u32_e32 v140, s24, v197
	ds_read_b128 v[72:75], v100
	ds_read_b128 v[84:87], v100 offset:1024
	ds_read_b128 v[96:99], v100 offset:2048
	ds_read_b128 v[100:103], v100 offset:3072
	ds_read_b128 v[112:115], v140
	ds_read_b128 v[116:119], v140 offset:1024
	ds_read_b128 v[128:131], v140 offset:2048
	ds_read_b128 v[140:143], v140 offset:3072
	s_add_u32 s14, s40, 0x40000
	s_addc_u32 s15, s41, 0
	s_mov_b32 m0, s74
	v_lshl_add_u64 v[240:241], s[14:15], 0, v[160:161]
	ds_read_b128 v[184:187], v200 offset:32768
	ds_read_b128 v[188:191], v200 offset:33792
	ds_read_b128 v[192:195], v200 offset:34816
	ds_read_b128 v[202:205], v200 offset:35840
	ds_read_b128 v[218:221], v200 offset:36864
	ds_read_b128 v[222:225], v200 offset:37888
	ds_read_b128 v[226:229], v200 offset:38912
	ds_read_b128 v[230:233], v200 offset:39936
	global_load_lds_dwordx4 v[240:241], off
	v_lshl_add_u64 v[240:241], s[14:15], 0, v[164:165]
	s_mov_b32 m0, s75
	s_nop 0
	global_load_lds_dwordx4 v[240:241], off
	s_cmp_eq_u32 s100, 0
	s_cbranch_scc1 .Lw8_8c
	s_waitcnt vmcnt(24)
	s_branch .Lwd_8c

; #define PG8_STAGE(bufoff, gbase, voff) do { _Pragma("unroll") for (int _i = 0; _i < 2; ++_i) \
;         __builtin_amdgcn_global_load_lds((const unsigned*)((const char*)(gbase) + (voff)[_i]), (PG8_LAS unsigned*)(lds + (bufoff) + ldsw + _i * 8192), 16, 0, 0); } while (0)
; #define PG8_LDA(dst, b, h) do { _Pragma("unroll") for (int m = 0; m < 4; ++m) _Pragma("unroll") for (int k = 0; k < 2; ++k) dst[m][k] = *(const PG8_LAS bf16x8*)(lds + PG8_SA(b, h) + aoff + m * 2048 + k * 1024); } while (0)
; #define PG8_LDB(dst, b, h) do { _Pragma("unroll") for (int n = 0; n < 2; ++n) _Pragma("unroll") for (int k = 0; k < 2; ++k) dst[n][k] = *(const PG8_LAS bf16x8*)(lds + PG8_SB(b, h) + boff + n * 2048 + k * 1024); } while (0)
; #define PG8_MMA(ai, bj, At, Bt) do { __builtin_amdgcn_s_setprio(1); _Pragma("unroll") for (int m = 0; m < 4; ++m) _Pragma("unroll") for (int n = 0; n < 2; ++n) _Pragma("unroll") for (int k = 0; k < 2; ++k) \
;         acc[ai][bj][m][n] = __builtin_amdgcn_mfma_f32_16x16x32_bf16(Bt[n][k], At[m][k], acc[ai][bj][m][n], 0, 0, 0); __builtin_amdgcn_s_setprio(0); } while (0)
; #define PG8_WAIT_V(n) asm volatile("s_waitcnt vmcnt(" #n ")" ::: "memory")
; #define PG8_WAIT_L(n) asm volatile("s_waitcnt lgkmcnt(" #n ")" ::: "memory")
; #define PG8_BAR __builtin_amdgcn_s_barrier()
; #define PG8_SCHED __builtin_amdgcn_sched_barrier(0)
; template <class Epi, class Sched, bool ALIGN_EPI = false, bool SP2 = false>
; __device__ __forceinline__ void gemm_phase(PG8_LAS unsigned char* lds, const Gemm g, const Sched& S, const Epi& E) {
;     ...
;             PG8_LDB(B0, 0, 0); PG8_LDB(B1, 0, 1); PG8_SCHED; PG8_LDA(At, 0, 0); PG8_STAGE(PG8_SA(1, 1), a1 + hstep, voffA);
;     ...
;             PG8_WAIT_V(8); PG8_WAIT_L(0); PG8_BAR; PG8_MMA(1, 0, At, B0); PG8_MMA(1, 1, At, B1); PG8_BAR; PG8_SCHED;
;             PG8_LDB(B0, 1, 0); PG8_LDB(B1, 1, 1); PG8_SCHED; PG8_LDA(At, 1, 0); PG8_STAGE(PG8_SA(0, 1), a2 + hstep, voffA);
;             PG8_WAIT_V(8); PG8_WAIT_L(0); PG8_BAR; PG8_MMA(0, 0, At, B0); PG8_MMA(0, 1, At, B1); PG8_BAR; PG8_SCHED;
;             PG8_LDA(At, 1, 1); PG8_STAGE(PG8_SB(1, 0), b3, voffB); PG8_STAGE(PG8_SB(1, 1), b3 + hstep, voffB); PG8_STAGE(PG8_SA(1, 0), a3, voffA);
;             PG8_WAIT_V(8); PG8_WAIT_L(0); PG8_BAR; PG8_MMA(1, 0, At, B0); PG8_MMA(1, 1, At, B1); PG8_BAR; PG8_SCHED;
.Lwd_8c:
	s_mov_b32 s100, 0
	s_waitcnt lgkmcnt(0)
	s_barrier
	s_setprio 1
	s_waitcnt lgkmcnt(0)
	v_mfma_f32_16x16x32_bf16 v[156:159], v[72:75], v[184:187], v[156:159]
	v_mfma_f32_16x16x32_bf16 v[152:155], v[96:99], v[184:187], v[152:155]
	v_mfma_f32_16x16x32_bf16 v[136:139], v[72:75], v[192:195], v[136:139]
	v_mfma_f32_16x16x32_bf16 v[132:135], v[96:99], v[192:195], v[132:135]
	v_mfma_f32_16x16x32_bf16 v[108:111], v[72:75], v[218:221], v[108:111]
	v_mfma_f32_16x16x32_bf16 v[104:107], v[96:99], v[218:221], v[104:107]
	v_mfma_f32_16x16x32_bf16 v[80:83], v[72:75], v[226:229], v[80:83]
	v_mfma_f32_16x16x32_bf16 v[76:79], v[96:99], v[226:229], v[76:79]
	v_mfma_f32_16x16x32_bf16 v[156:159], v[84:87], v[188:191], v[156:159]
	v_mfma_f32_16x16x32_bf16 v[152:155], v[100:103], v[188:191], v[152:155]
	v_mfma_f32_16x16x32_bf16 v[136:139], v[84:87], v[202:205], v[136:139]
	v_mfma_f32_16x16x32_bf16 v[132:135], v[100:103], v[202:205], v[132:135]
	v_mfma_f32_16x16x32_bf16 v[108:111], v[84:87], v[222:225], v[108:111]
	v_mfma_f32_16x16x32_bf16 v[104:107], v[100:103], v[222:225], v[104:107]
	v_mfma_f32_16x16x32_bf16 v[80:83], v[84:87], v[230:233], v[80:83]
	v_mfma_f32_16x16x32_bf16 v[76:79], v[100:103], v[230:233], v[76:79]
	s_setprio 0
	s_setprio 1
	v_mfma_f32_16x16x32_bf16 v[148:151], v[112:115], v[184:187], v[148:151]
	v_mfma_f32_16x16x32_bf16 v[144:147], v[128:131], v[184:187], v[144:147]
	v_mfma_f32_16x16x32_bf16 v[124:127], v[112:115], v[192:195], v[124:127]
	v_mfma_f32_16x16x32_bf16 v[120:123], v[128:131], v[192:195], v[120:123]
	v_mfma_f32_16x16x32_bf16 v[92:95], v[112:115], v[218:221], v[92:95]
	v_mfma_f32_16x16x32_bf16 v[88:91], v[128:131], v[218:221], v[88:91]
	v_mfma_f32_16x16x32_bf16 v[68:71], v[112:115], v[226:229], v[68:71]
	v_mfma_f32_16x16x32_bf16 v[64:67], v[128:131], v[226:229], v[64:67]
	v_mfma_f32_16x16x32_bf16 v[148:151], v[116:119], v[188:191], v[148:151]
	v_mfma_f32_16x16x32_bf16 v[144:147], v[140:143], v[188:191], v[144:147]
	v_mfma_f32_16x16x32_bf16 v[124:127], v[116:119], v[202:205], v[124:127]
	v_mfma_f32_16x16x32_bf16 v[120:123], v[140:143], v[202:205], v[120:123]
	v_mfma_f32_16x16x32_bf16 v[92:95], v[116:119], v[222:225], v[92:95]
	v_mfma_f32_16x16x32_bf16 v[88:91], v[140:143], v[222:225], v[88:91]
	v_mfma_f32_16x16x32_bf16 v[68:71], v[116:119], v[230:233], v[68:71]
	v_mfma_f32_16x16x32_bf16 v[64:67], v[140:143], v[230:233], v[64:67]
	s_setprio 0
	s_barrier
	s_add_i32 s14, s17, s51
	v_lshl_add_u64 v[206:207], v[206:207], 0, s[46:47]
	s_mov_b32 m0, s14
	ds_read_b128 v[184:187], v200 offset:49152
	ds_read_b128 v[188:191], v200 offset:50176
	ds_read_b128 v[192:195], v200 offset:51200
	ds_read_b128 v[202:205], v200 offset:52224
	ds_read_b128 v[218:221], v200 offset:53248
	ds_read_b128 v[222:225], v200 offset:54272
	ds_read_b128 v[226:229], v200 offset:55296
	ds_read_b128 v[230:233], v200 offset:56320
	global_load_lds_dwordx4 v[206:207], off
	s_add_i32 m0, s14, 0x2000
	s_add_u32 s14, s18, 0x40080
	v_lshl_add_u64 v[206:207], v[234:235], 0, s[46:47]
	s_addc_u32 s15, s19, 0
	s_add_i32 s17, s24, s51
	global_load_lds_dwordx4 v[206:207], off
	v_lshl_add_u64 v[206:207], s[14:15], 0, v[162:163]
	s_mov_b32 m0, s17
	s_nop 0
	global_load_lds_dwordx4 v[206:207], off
	v_lshl_add_u64 v[206:207], s[14:15], 0, v[166:167]
	s_add_i32 m0, s17, 0x2000
	s_nop 0
	global_load_lds_dwordx4 v[206:207], off
	v_lshl_add_u64 v[206:207], v[236:237], 0, s[46:47]
	s_mov_b32 m0, s78
	s_nop 0
	global_load_lds_dwordx4 v[206:207], off
	v_lshl_add_u64 v[206:207], v[238:239], 0, s[46:47]
	s_mov_b32 m0, s79
	s_nop 0
	global_load_lds_dwordx4 v[206:207], off
	s_waitcnt vmcnt(8)
	s_waitcnt lgkmcnt(0)
	s_barrier
	s_setprio 1
	s_waitcnt lgkmcnt(0)
	v_mfma_f32_16x16x32_bf16 v[60:63], v[72:75], v[184:187], v[60:63]
	v_mfma_f32_16x16x32_bf16 v[56:59], v[96:99], v[184:187], v[56:59]
	v_mfma_f32_16x16x32_bf16 v[44:47], v[72:75], v[192:195], v[44:47]
	v_mfma_f32_16x16x32_bf16 v[40:43], v[96:99], v[192:195], v[40:43]
	v_mfma_f32_16x16x32_bf16 v[28:31], v[72:75], v[218:221], v[28:31]
	v_mfma_f32_16x16x32_bf16 v[24:27], v[96:99], v[218:221], v[24:27]
	v_mfma_f32_16x16x32_bf16 v[12:15], v[72:75], v[226:229], v[12:15]
	v_mfma_f32_16x16x32_bf16 v[8:11], v[96:99], v[226:229], v[8:11]
	v_mfma_f32_16x16x32_bf16 v[60:63], v[84:87], v[188:191], v[60:63]
	v_mfma_f32_16x16x32_bf16 v[56:59], v[100:103], v[188:191], v[56:59]
	v_mfma_f32_16x16x32_bf16 v[44:47], v[84:87], v[202:205], v[44:47]
	v_mfma_f32_16x16x32_bf16 v[40:43], v[100:103], v[202:205], v[40:43]
	v_mfma_f32_16x16x32_bf16 v[28:31], v[84:87], v[222:225], v[28:31]
	v_mfma_f32_16x16x32_bf16 v[24:27], v[100:103], v[222:225], v[24:27]
	v_mfma_f32_16x16x32_bf16 v[12:15], v[84:87], v[230:233], v[12:15]
	v_mfma_f32_16x16x32_bf16 v[8:11], v[100:103], v[230:233], v[8:11]
	s_setprio 0
	s_setprio 1
	v_mfma_f32_16x16x32_bf16 v[52:55], v[112:115], v[184:187], v[52:55]
	v_mfma_f32_16x16x32_bf16 v[48:51], v[128:131], v[184:187], v[48:51]
	v_mfma_f32_16x16x32_bf16 v[36:39], v[112:115], v[192:195], v[36:39]
	v_mfma_f32_16x16x32_bf16 v[32:35], v[128:131], v[192:195], v[32:35]
	v_mfma_f32_16x16x32_bf16 v[20:23], v[112:115], v[218:221], v[20:23]
	v_mfma_f32_16x16x32_bf16 v[16:19], v[128:131], v[218:221], v[16:19]
	v_mfma_f32_16x16x32_bf16 v[4:7], v[112:115], v[226:229], v[4:7]
	v_mfma_f32_16x16x32_bf16 v[0:3], v[128:131], v[226:229], v[0:3]
	v_mfma_f32_16x16x32_bf16 v[52:55], v[116:119], v[188:191], v[52:55]
	v_mfma_f32_16x16x32_bf16 v[48:51], v[140:143], v[188:191], v[48:51]
	v_mfma_f32_16x16x32_bf16 v[36:39], v[116:119], v[202:205], v[36:39]
	v_mfma_f32_16x16x32_bf16 v[32:35], v[140:143], v[202:205], v[32:35]
	v_mfma_f32_16x16x32_bf16 v[20:23], v[116:119], v[222:225], v[20:23]
	v_mfma_f32_16x16x32_bf16 v[16:19], v[140:143], v[222:225], v[16:19]
	v_mfma_f32_16x16x32_bf16 v[4:7], v[116:119], v[230:233], v[4:7]
	v_mfma_f32_16x16x32_bf16 v[0:3], v[140:143], v[230:233], v[0:3]
	s_setprio 0
	s_barrier
	s_add_i32 s16, s16, 2
	s_add_u32 s38, s38, 0x100
	s_addc_u32 s39, s39, 0
	s_add_u32 s72, s72, 0x100
	s_addc_u32 s33, s33, 0
	s_cmp_gt_u32 s16, 13
	s_cbranch_scc0 .LBB0_637
	s_and_b64 vcc, exec, s[48:49]
	s_cbranch_vccz .LBB0_640
	s_barrier
.LBB0_640:
	s_mov_b32 s98, 0
	s_cmp_eq_u64 s[36:37], 0
	s_cbranch_scc1 .Les8_skip
	s_mov_b32 s101, m0
	s_add_u32 s14, s56, 0x40080
	s_addc_u32 s15, s57, 0
	v_lshl_add_u64 v[250:251], s[14:15], 0, v[176:177]
	s_add_i32 m0, s61, 0xc000
	s_nop 0
	global_load_lds_dwordx4 v[250:251], off
	v_lshl_add_u64 v[250:251], s[14:15], 0, v[178:179]
	s_add_i32 m0, s61, 0xe000
	s_nop 0
	global_load_lds_dwordx4 v[250:251], off
	s_mov_b32 m0, s101
